# gdnpre block inversion: scalar LDS operand reads of the f32 MFMA chains issued a whole block ahead (spare VGPRs, counted lgkmcnt)
# baseline (speedup 1.0000x reference)
.LBB0_275:
	s_or_b64 exec, exec, s[12:13]
	s_waitcnt lgkmcnt(0)
	v_sub_f32_e32 v4, v15, v4
	v_mul_f32_e32 v4, 0x3fb8aa3b, v4
	v_exp_f32_e32 v4, v4
	v_cmp_gt_i32_e64 s[40:41], v10, v48
	v_mul_f32_e32 v11, v6, v11
	v_mul_f32_e32 v17, v7, v23
	v_mul_f32_e32 v22, v8, v22
	v_mul_f32_e32 v15, v7, v20
	v_mul_f32_e32 v20, v6, v21
	v_cndmask_b32_e64 v4, v4, 0, s[40:41]
	v_mul_f32_e32 v6, v9, v3
	v_mul_f32_e32 v8, v8, v24
	v_cvt_pk_bf16_f32 v7, v22, v6
	v_cvt_pk_bf16_f32 v6, v11, v17
	v_mul_f32_e32 v11, v9, v4
	v_cvt_pk_bf16_f32 v8, v11, v8
	v_mul_f32_e32 v11, v5, v13
	v_mul_f32_e32 v3, v11, v3
	v_cndmask_b32_e64 v3, 0, v3, s[40:41]
	ds_write_b32 v2, v3 offset:12
	v_mul_f32_e32 v2, v5, v12
	v_mul_f32_e32 v2, v2, v4
	v_sub_u32_e32 v3, v16, v48
	v_cndmask_b32_e64 v2, 0, v2, s[0:1]
	v_lshl_add_u32 v3, v3, 2, 0
	ds_write_b32 v3, v2 offset:16892
	v_lshlrev_b32_e32 v2, 7, v10
	v_mov_b32_e32 v3, v0
	v_lshl_add_u64 v[4:5], v[30:31], 0, v[2:3]
	v_xor_b32_e32 v2, 0x1f80, v2
	v_cvt_pk_bf16_f32 v9, v15, v20
	v_lshl_add_u64 v[2:3], v[46:47], 0, v[2:3]
	global_store_dwordx2 v[4:5], v[6:7], off
	global_store_dwordx2 v[2:3], v[8:9], off
	s_waitcnt lgkmcnt(0)
	s_barrier
	s_and_saveexec_b64 s[0:1], vcc
	s_cbranch_execz .LBB0_277
	s_movk_i32 s2, 0x4100
	v_mul_lo_u32 v3, v68, s2
	v_add_u32_e32 v4, 0, v3
	v_and_b32_e32 v3, 48, v1
	v_mul_u32_u24_e32 v5, 0x104, v3
	v_lshlrev_b32_e32 v6, 2, v3
	v_add3_u32 v5, v4, v5, v6
	ds_read_b32 v16, v5 offset:260
	ds_read_b64 v[20:21], v5 offset:520
	ds_read_b32 v17, v5 offset:780
	ds_read_b64 v[22:23], v5 offset:784
	ds_read_b128 v[46:49], v5 offset:1040
	ds_read_b32 v24, v5 offset:1300
	ds_read_b64 v[30:31], v5 offset:1304
	ds_read_b64 v[50:51], v5 offset:1312
	ds_read_b64 v[52:53], v5 offset:1560
	ds_read_b128 v[54:57], v5 offset:1568
	ds_read_b32 v25, v5 offset:1820
	ds_read_b128 v[58:61], v5 offset:1824
	ds_read_b64 v[62:63], v5 offset:1840
	ds_read_b128 v[64:67], v5 offset:2080
	ds_read_b128 v[70:73], v5 offset:2096
	ds_read_b32 v74, v5 offset:2340
	ds_read_b64 v[76:77], v5 offset:2344
	ds_read_b128 v[78:81], v5 offset:2352
	ds_read_b64 v[82:83], v5 offset:2368
	ds_read_b64 v[84:85], v5 offset:2600
	ds_read_b128 v[90:93], v5 offset:2608
	ds_read_b128 v[152:155], v5 offset:2624
	ds_read_b32 v75, v5 offset:2860
	ds_read_b128 v[156:159], v5 offset:2864
	ds_read_b128 v[160:163], v5 offset:2880
	ds_read_b64 v[86:87], v5 offset:2896
	ds_read_b128 v[164:167], v5 offset:3120
	ds_read_b128 v[168:171], v5 offset:3136
	ds_read_b128 v[234:237], v5 offset:3152
	ds_read_b32 v88, v5 offset:3380
	ds_read_b64 v[94:95], v5 offset:3384
	ds_read_b128 v[238:241], v5 offset:3392
	ds_read_b128 v[250:253], v5 offset:3408
	ds_read_b64 v[242:243], v5 offset:3424
	v_cmp_eq_u32_e32 vcc, 0, v37
	v_cndmask_b32_e64 v27, 0, 1.0, vcc
	v_cmp_eq_u32_e32 vcc, 1, v37
	s_waitcnt lgkmcnt(15)
	v_cndmask_b32_e64 v33, 0, 1.0, vcc
	v_fma_f32 v33, -v27, v16, v33
	v_cmp_eq_u32_e32 vcc, 2, v37
	s_waitcnt lgkmcnt(15)
	v_cndmask_b32_e64 v39, 0, 1.0, vcc
	v_fma_f32 v39, -v27, v20, v39
	v_fma_f32 v39, -v33, v21, v39
	v_cmp_eq_u32_e32 vcc, 3, v37
	s_waitcnt lgkmcnt(15)
	v_cndmask_b32_e64 v11, 0, 1.0, vcc
	v_fma_f32 v11, -v27, v17, v11
	v_fma_f32 v11, -v33, v22, v11
	v_fma_f32 v11, -v39, v23, v11
	v_cmp_eq_u32_e32 vcc, 4, v37
	s_waitcnt lgkmcnt(15)
	v_cndmask_b32_e64 v15, 0, 1.0, vcc
	v_fma_f32 v15, -v27, v46, v15
	v_fma_f32 v15, -v33, v47, v15
	v_fma_f32 v15, -v39, v48, v15
	v_fma_f32 v15, -v11, v49, v15
	v_cmp_eq_u32_e32 vcc, 5, v37
	s_waitcnt lgkmcnt(15)
	v_cndmask_b32_e64 v29, 0, 1.0, vcc
	v_fma_f32 v29, -v27, v24, v29
	v_fma_f32 v29, -v33, v30, v29
	v_fma_f32 v29, -v39, v31, v29
	v_fma_f32 v29, -v11, v50, v29
	v_fma_f32 v29, -v15, v51, v29
	v_cmp_eq_u32_e32 vcc, 6, v37
	s_waitcnt lgkmcnt(15)
	v_cndmask_b32_e64 v69, 0, 1.0, vcc
	v_fma_f32 v69, -v27, v52, v69
	v_fma_f32 v69, -v33, v53, v69
	v_fma_f32 v69, -v39, v54, v69
	v_fma_f32 v69, -v11, v55, v69
	v_fma_f32 v69, -v15, v56, v69
	v_fma_f32 v69, -v29, v57, v69
	v_cmp_eq_u32_e32 vcc, 7, v37
	s_waitcnt lgkmcnt(15)
	v_cndmask_b32_e64 v151, 0, 1.0, vcc
	v_fma_f32 v151, -v27, v25, v151
	v_fma_f32 v151, -v33, v58, v151
	v_fma_f32 v151, -v39, v59, v151
	v_fma_f32 v151, -v11, v60, v151
	v_fma_f32 v151, -v15, v61, v151
	v_fma_f32 v151, -v29, v62, v151
	v_fma_f32 v151, -v69, v63, v151
	v_cmp_eq_u32_e32 vcc, 8, v37
	s_waitcnt lgkmcnt(15)
	v_cndmask_b32_e64 v233, 0, 1.0, vcc
	v_fma_f32 v233, -v27, v64, v233
	v_fma_f32 v233, -v33, v65, v233
	v_fma_f32 v233, -v39, v66, v233
	v_fma_f32 v233, -v11, v67, v233
	v_fma_f32 v233, -v15, v70, v233
	v_fma_f32 v233, -v29, v71, v233
	v_fma_f32 v233, -v69, v72, v233
	v_fma_f32 v233, -v151, v73, v233
	v_cmp_eq_u32_e32 vcc, 9, v37
	s_waitcnt lgkmcnt(15)
	v_cndmask_b32_e64 v249, 0, 1.0, vcc
	v_fma_f32 v249, -v27, v74, v249
	v_fma_f32 v249, -v33, v76, v249
	v_fma_f32 v249, -v39, v77, v249
	v_fma_f32 v249, -v11, v78, v249
	v_fma_f32 v249, -v15, v79, v249
	v_fma_f32 v249, -v29, v80, v249
	v_fma_f32 v249, -v69, v81, v249
	v_fma_f32 v249, -v151, v82, v249
	v_fma_f32 v249, -v233, v83, v249
	ds_read_b64 v[16:17], v5 offset:3640
	ds_read_b128 v[20:23], v5 offset:3648
	ds_read_b128 v[46:49], v5 offset:3664
	ds_read_b128 v[50:53], v5 offset:3680
	ds_read_b32 v244, v5 offset:3900
	ds_read_b128 v[54:57], v5 offset:3904
	ds_read_b128 v[58:61], v5 offset:3920
	ds_read_b128 v[62:65], v5 offset:3936
	ds_read_b64 v[24:25], v5 offset:3952
	v_cmp_eq_u32_e32 vcc, 10, v37
	s_waitcnt lgkmcnt(15)
	v_cndmask_b32_e64 v6, 0, 1.0, vcc
	v_fma_f32 v6, -v27, v84, v6
	v_fma_f32 v6, -v33, v85, v6
	v_fma_f32 v6, -v39, v90, v6
	v_fma_f32 v6, -v11, v91, v6
	v_fma_f32 v6, -v15, v92, v6
	v_fma_f32 v6, -v29, v93, v6
	v_fma_f32 v6, -v69, v152, v6
	v_fma_f32 v6, -v151, v153, v6
	v_fma_f32 v6, -v233, v154, v6
	v_fma_f32 v6, -v249, v155, v6
	v_cmp_eq_u32_e32 vcc, 11, v37
	s_waitcnt lgkmcnt(15)
	v_cndmask_b32_e64 v7, 0, 1.0, vcc
	v_fma_f32 v7, -v27, v75, v7
	v_fma_f32 v7, -v33, v156, v7
	v_fma_f32 v7, -v39, v157, v7
	v_fma_f32 v7, -v11, v158, v7
	v_fma_f32 v7, -v15, v159, v7
	v_fma_f32 v7, -v29, v160, v7
	v_fma_f32 v7, -v69, v161, v7
	v_fma_f32 v7, -v151, v162, v7
	v_fma_f32 v7, -v233, v163, v7
	v_fma_f32 v7, -v249, v86, v7
	v_fma_f32 v7, -v6, v87, v7
	v_cmp_eq_u32_e32 vcc, 12, v37
	s_waitcnt lgkmcnt(14)
	v_cndmask_b32_e64 v8, 0, 1.0, vcc
	v_fma_f32 v8, -v27, v164, v8
	v_fma_f32 v8, -v33, v165, v8
	v_fma_f32 v8, -v39, v166, v8
	v_fma_f32 v8, -v11, v167, v8
	v_fma_f32 v8, -v15, v168, v8
	v_fma_f32 v8, -v29, v169, v8
	v_fma_f32 v8, -v69, v170, v8
	v_fma_f32 v8, -v151, v171, v8
	v_fma_f32 v8, -v233, v234, v8
	v_fma_f32 v8, -v249, v235, v8
	v_fma_f32 v8, -v6, v236, v8
	v_fma_f32 v8, -v7, v237, v8
	v_cmp_eq_u32_e32 vcc, 13, v37
	s_waitcnt lgkmcnt(9)
	v_cndmask_b32_e64 v9, 0, 1.0, vcc
	v_fma_f32 v9, -v27, v88, v9
	v_fma_f32 v9, -v33, v94, v9
	v_fma_f32 v9, -v39, v95, v9
	v_fma_f32 v9, -v11, v238, v9
	v_fma_f32 v9, -v15, v239, v9
	v_fma_f32 v9, -v29, v240, v9
	v_fma_f32 v9, -v69, v241, v9
	v_fma_f32 v9, -v151, v250, v9
	v_fma_f32 v9, -v233, v251, v9
	v_fma_f32 v9, -v249, v252, v9
	v_fma_f32 v9, -v6, v253, v9
	v_fma_f32 v9, -v7, v242, v9
	v_fma_f32 v9, -v8, v243, v9
	v_cmp_eq_u32_e32 vcc, 14, v37
	s_waitcnt lgkmcnt(5)
	v_cndmask_b32_e64 v12, 0, 1.0, vcc
	v_fma_f32 v12, -v27, v16, v12
	v_fma_f32 v12, -v33, v17, v12
	v_fma_f32 v12, -v39, v20, v12
	v_fma_f32 v12, -v11, v21, v12
	v_fma_f32 v12, -v15, v22, v12
	v_fma_f32 v12, -v29, v23, v12
	v_fma_f32 v12, -v69, v46, v12
	v_fma_f32 v12, -v151, v47, v12
	v_fma_f32 v12, -v233, v48, v12
	v_fma_f32 v12, -v249, v49, v12
	v_fma_f32 v12, -v6, v50, v12
	v_fma_f32 v12, -v7, v51, v12
	v_fma_f32 v12, -v8, v52, v12
	v_fma_f32 v12, -v9, v53, v12
	v_cmp_eq_u32_e32 vcc, 15, v37
	s_waitcnt lgkmcnt(0)
	v_cndmask_b32_e64 v13, 0, 1.0, vcc
	v_fma_f32 v13, -v27, v244, v13
	v_fma_f32 v13, -v33, v54, v13
	v_fma_f32 v13, -v39, v55, v13
	v_fma_f32 v13, -v11, v56, v13
	v_fma_f32 v13, -v15, v57, v13
	v_fma_f32 v13, -v29, v58, v13
	v_fma_f32 v13, -v69, v59, v13
	v_fma_f32 v13, -v151, v60, v13
	v_fma_f32 v13, -v233, v61, v13
	v_fma_f32 v13, -v249, v62, v13
	v_fma_f32 v13, -v6, v63, v13
	v_fma_f32 v13, -v7, v64, v13
	v_fma_f32 v13, -v8, v65, v13
	v_fma_f32 v13, -v9, v24, v13
	v_fma_f32 v13, -v12, v25, v13
	v_add_u32_e32 v5, v5, v41
	ds_write_b32 v5, v27
	ds_write_b32 v5, v33 offset:260
	ds_write_b32 v5, v39 offset:520
	ds_write_b32 v5, v11 offset:780
	ds_write_b32 v5, v15 offset:1040
	ds_write_b32 v5, v29 offset:1300
	ds_write_b32 v5, v69 offset:1560
	ds_write_b32 v5, v151 offset:1820
	ds_write_b32 v5, v233 offset:2080
	ds_write_b32 v5, v249 offset:2340
	ds_write_b32 v5, v6 offset:2600
	ds_write_b32 v5, v7 offset:2860
	ds_write_b32 v5, v8 offset:3120
	ds_write_b32 v5, v9 offset:3380
	ds_write_b32 v5, v12 offset:3640
	ds_write_b32 v5, v13 offset:3900
	v_mul_u32_u24_e32 v2, 0x104, v37
	s_movk_i32 s2, 0x1040
	v_add3_u32 v2, v2, v4, s2
	s_movk_i32 s2, 0x104
	v_add_u32_e32 v5, v4, v41
	v_lshl_add_u32 v4, v45, 2, v2
	ds_read2_b32 v[152:153], v4 offset1:4
	ds_read2_b32 v[154:155], v4 offset0:8 offset1:12
	v_add_u32_e32 v11, v2, v3
	ds_read2_b32 v[156:157], v11 offset0:16 offset1:17
	ds_read2_b32 v[158:159], v11 offset0:18 offset1:19
	v_mad_u32_u24 v2, v45, s2, v5
	ds_read_b32 v233, v2
	ds_read_b32 v244, v2 offset:1040
	ds_read_b32 v249, v2 offset:2080
	ds_read_b32 v160, v2 offset:3120
	s_nop 0
	s_nop 0
	s_nop 0
	s_nop 0
	s_waitcnt lgkmcnt(3)
	v_mfma_f32_16x16x4_f32 v[6:9], v152, v233, 0
	s_nop 0
	s_nop 0
	s_nop 0
	s_movk_i32 s2, 0x410
	v_mad_u32_u24 v3, v45, s2, v5
	v_add_u32_e32 v48, 0x2140, v11
	s_nop 0
	s_waitcnt lgkmcnt(2)
	v_mfma_f32_16x16x4_f32 v[6:9], v153, v244, v[6:9]
	s_nop 0
	s_nop 0
	s_waitcnt lgkmcnt(1)
	v_mfma_f32_16x16x4_f32 v[6:9], v154, v249, v[6:9]
	s_nop 0
	s_waitcnt lgkmcnt(0)
	v_mfma_f32_16x16x4_f32 v[6:9], v155, v160, v[6:9]
	s_nop 0
	s_nop 8
	v_mfma_f32_16x16x4_f32 v[20:23], v156, v6, 0
	v_mfma_f32_16x16x4_f32 v[20:23], v157, v7, v[20:23]
	s_nop 0
	s_nop 0
	v_mfma_f32_16x16x4_f32 v[20:23], v158, v8, v[20:23]
	v_mfma_f32_16x16x4_f32 v[6:9], v159, v9, v[20:23]
	s_nop 9
	v_xor_b32_e32 v6, 0x80000000, v6
	v_xor_b32_e32 v5, 0x80000000, v7
	v_add_u32_e32 v7, 0x1000, v3
	ds_write2_b32 v7, v6, v5 offset0:16 offset1:81
	v_xor_b32_e32 v5, 0x80000000, v8
	v_xor_b32_e32 v6, 0x80000000, v9
	ds_write2_b32 v7, v5, v6 offset0:146 offset1:211
	ds_read_b32 v161, v4 offset:4224
	ds_read_b32 v152, v2 offset:4160
	ds_read_b32 v153, v4 offset:4240
	ds_read_b32 v154, v2 offset:5200
	ds_read_b32 v155, v4 offset:4256
	ds_read_b32 v156, v2 offset:6240
	ds_read_b32 v157, v4 offset:4272
	ds_read_b32 v158, v2 offset:7280
	v_add_u32_e32 v6, 0x1000, v4
	ds_read2_b32 v[162:163], v6 offset0:16 offset1:20
	ds_read2_b32 v[164:165], v6 offset0:24 offset1:28
	s_nop 0
	s_nop 0
	s_nop 0
	s_waitcnt lgkmcnt(1)
	v_mfma_f32_16x16x4_f32 v[6:9], v162, v233, 0
	s_nop 0
	s_nop 0
	v_add_u32_e32 v5, 0x10c0, v11
	ds_read2_b32 v[166:167], v5 offset1:1
	v_mfma_f32_16x16x4_f32 v[6:9], v163, v244, v[6:9]
	s_nop 0
	s_waitcnt lgkmcnt(1)
	v_mfma_f32_16x16x4_f32 v[6:9], v164, v249, v[6:9]
	v_add_u32_e32 v16, 0x10c8, v11
	ds_read2_b32 v[162:163], v16 offset1:1
	v_add_u32_e32 v11, 0x2148, v11
	v_mfma_f32_16x16x4_f32 v[6:9], v165, v160, v[6:9]
	s_nop 0
	v_mfma_f32_16x16x4_f32 v[6:9], v161, v152, v[6:9]
	s_nop 0
	s_nop 0
	s_nop 0
	v_mfma_f32_16x16x4_f32 v[6:9], v153, v154, v[6:9]
	s_nop 0
	s_nop 0
	s_nop 0
	v_mfma_f32_16x16x4_f32 v[6:9], v155, v156, v[6:9]
	s_nop 0
	s_nop 0
	s_nop 0
	v_mfma_f32_16x16x4_f32 v[6:9], v157, v158, v[6:9]
	s_nop 0
	s_nop 0
	s_nop 7
	s_waitcnt lgkmcnt(1)
	v_mfma_f32_16x16x4_f32 v[20:23], v166, v6, 0
	v_mfma_f32_16x16x4_f32 v[20:23], v167, v7, v[20:23]
	s_nop 0
	s_nop 0
	s_waitcnt lgkmcnt(0)
	v_mfma_f32_16x16x4_f32 v[20:23], v162, v8, v[20:23]
	v_mfma_f32_16x16x4_f32 v[6:9], v163, v9, v[20:23]
	s_nop 9
	v_xor_b32_e32 v6, 0x80000000, v6
	ds_write_b32 v3, v6 offset:8320
	v_xor_b32_e32 v6, 0x80000000, v7
	ds_write_b32 v3, v6 offset:8580
	v_xor_b32_e32 v6, 0x80000000, v8
	ds_write_b32 v3, v6 offset:8840
	v_xor_b32_e32 v6, 0x80000000, v9
	ds_write_b32 v3, v6 offset:9100
	ds_read_b32 v153, v2 offset:4224
	ds_read_b32 v155, v4 offset:4224
	ds_read_b32 v157, v4 offset:4240
	ds_read_b32 v159, v4 offset:4256
	ds_read_b32 v161, v4 offset:4272
	ds_read_b32 v162, v2 offset:5264
	ds_read_b32 v163, v2 offset:6304
	ds_read_b32 v164, v2 offset:7344
	ds_read2_b32 v[166:167], v5 offset1:1
	ds_read2_b32 v[168:169], v16 offset1:1
	s_nop 0
	s_nop 0
	s_nop 0
	s_nop 0
	s_nop 0
	s_nop 0
	s_waitcnt lgkmcnt(8)
	v_mfma_f32_16x16x4_f32 v[6:9], v155, v153, 0
	s_nop 0
	s_nop 0
	s_nop 0
	s_nop 0
	s_waitcnt lgkmcnt(4)
	v_mfma_f32_16x16x4_f32 v[6:9], v157, v162, v[6:9]
	s_nop 0
	s_waitcnt lgkmcnt(3)
	v_mfma_f32_16x16x4_f32 v[6:9], v159, v163, v[6:9]
	s_nop 0
	s_nop 0
	s_waitcnt lgkmcnt(2)
	v_mfma_f32_16x16x4_f32 v[6:9], v161, v164, v[6:9]
	s_nop 0
	s_nop 8
	s_waitcnt lgkmcnt(1)
	v_mfma_f32_16x16x4_f32 v[20:23], v166, v6, 0
	v_mfma_f32_16x16x4_f32 v[20:23], v167, v7, v[20:23]
	s_nop 0
	s_nop 0
	s_waitcnt lgkmcnt(0)
	v_mfma_f32_16x16x4_f32 v[20:23], v168, v8, v[20:23]
	v_mfma_f32_16x16x4_f32 v[6:9], v169, v9, v[20:23]
	s_nop 9
	v_xor_b32_e32 v5, 0x80000000, v6
	ds_write_b32 v3, v5 offset:8384
	v_xor_b32_e32 v5, 0x80000000, v7
	ds_write_b32 v3, v5 offset:8644
	v_xor_b32_e32 v5, 0x80000000, v8
	ds_write_b32 v3, v5 offset:8904
	v_xor_b32_e32 v5, 0x80000000, v9
	ds_write_b32 v3, v5 offset:9164
	ds_read_b32 v155, v4 offset:8384
	ds_read_b32 v157, v4 offset:8400
	ds_read_b32 v159, v4 offset:8416
	ds_read_b32 v161, v4 offset:8432
	ds_read_b32 v165, v4 offset:8448
	ds_read_b32 v166, v2 offset:8320
	ds_read_b32 v167, v4 offset:8464
	ds_read_b32 v168, v2 offset:9360
	ds_read_b32 v169, v4 offset:8480
	ds_read_b32 v170, v2 offset:10400
	ds_read_b32 v171, v4 offset:8496
	ds_read_b32 v234, v2 offset:11440
	ds_read2_b32 v[236:237], v48 offset1:1
	ds_read2_b32 v[238:239], v11 offset1:1
	v_add_u32_e32 v5, 0x2000, v4
	ds_read2_b32 v[240:241], v5 offset0:32 offset1:36
	s_nop 0
	ds_read2_b32 v[242:243], v5 offset0:40 offset1:44
	s_nop 0
	s_nop 0
	s_waitcnt lgkmcnt(1)
	v_mfma_f32_16x16x4_f32 v[6:9], v240, v233, 0
	s_nop 0
	v_mfma_f32_16x16x4_f32 v[6:9], v241, v244, v[6:9]
	s_nop 0
	s_waitcnt lgkmcnt(0)
	v_mfma_f32_16x16x4_f32 v[6:9], v242, v249, v[6:9]
	v_mfma_f32_16x16x4_f32 v[6:9], v243, v160, v[6:9]
	s_nop 0
	v_mfma_f32_16x16x4_f32 v[6:9], v155, v152, v[6:9]
	s_nop 0
	s_nop 0
	v_mfma_f32_16x16x4_f32 v[6:9], v157, v154, v[6:9]
	s_nop 0
	s_nop 0
	v_mfma_f32_16x16x4_f32 v[6:9], v159, v156, v[6:9]
	s_nop 0
	s_nop 0
	v_mfma_f32_16x16x4_f32 v[6:9], v161, v158, v[6:9]
	s_nop 0
	s_nop 0
	s_nop 0
	v_mfma_f32_16x16x4_f32 v[6:9], v165, v166, v[6:9]
	s_nop 0
	s_nop 0
	s_nop 0
	v_mfma_f32_16x16x4_f32 v[6:9], v167, v168, v[6:9]
	s_nop 0
	s_nop 0
	s_nop 0
	v_mfma_f32_16x16x4_f32 v[6:9], v169, v170, v[6:9]
	s_nop 0
	s_nop 0
	s_nop 0
	v_mfma_f32_16x16x4_f32 v[6:9], v171, v234, v[6:9]
	s_nop 0
	s_nop 0
	s_nop 7
	v_mfma_f32_16x16x4_f32 v[20:23], v236, v6, 0
	v_mfma_f32_16x16x4_f32 v[20:23], v237, v7, v[20:23]
	s_nop 0
	s_nop 0
	v_mfma_f32_16x16x4_f32 v[20:23], v238, v8, v[20:23]
	v_mfma_f32_16x16x4_f32 v[6:9], v239, v9, v[20:23]
	s_nop 9
	v_xor_b32_e32 v5, 0x80000000, v6
	ds_write_b32 v3, v5 offset:12480
	v_xor_b32_e32 v5, 0x80000000, v7
	ds_write_b32 v3, v5 offset:12740
	v_xor_b32_e32 v5, 0x80000000, v8
	ds_write_b32 v3, v5 offset:13000
	v_xor_b32_e32 v5, 0x80000000, v9
	ds_write_b32 v3, v5 offset:13260
	ds_read_b32 v152, v4 offset:8384
	ds_read_b32 v165, v4 offset:8400
	ds_read_b32 v233, v4 offset:8416
	ds_read_b32 v244, v4 offset:8432
	ds_read_b32 v249, v4 offset:8448
	ds_read_b32 v154, v2 offset:8384
	ds_read_b32 v155, v4 offset:8464
	ds_read_b32 v156, v2 offset:9424
	ds_read_b32 v157, v4 offset:8480
	ds_read_b32 v158, v2 offset:10464
	ds_read_b32 v159, v4 offset:8496
	ds_read_b32 v160, v2 offset:11504
	ds_read2_b32 v[166:167], v48 offset1:1
	ds_read2_b32 v[168:169], v11 offset1:1
	s_nop 0
	s_nop 0
	s_nop 0
	s_nop 0
	s_nop 0
	s_waitcnt lgkmcnt(13)
	v_mfma_f32_16x16x4_f32 v[6:9], v152, v153, 0
	s_nop 0
	s_waitcnt lgkmcnt(12)
	v_mfma_f32_16x16x4_f32 v[6:9], v165, v162, v[6:9]
	s_nop 0
	s_nop 0
	s_nop 0
	s_waitcnt lgkmcnt(11)
	v_mfma_f32_16x16x4_f32 v[6:9], v233, v163, v[6:9]
	s_nop 0
	s_waitcnt lgkmcnt(10)
	v_mfma_f32_16x16x4_f32 v[6:9], v244, v164, v[6:9]
	s_nop 0
	s_waitcnt lgkmcnt(8)
	v_mfma_f32_16x16x4_f32 v[6:9], v249, v154, v[6:9]
	s_nop 0
	s_nop 0
	s_nop 0
	s_waitcnt lgkmcnt(6)
	v_mfma_f32_16x16x4_f32 v[6:9], v155, v156, v[6:9]
	s_nop 0
	s_nop 0
	s_nop 0
	s_waitcnt lgkmcnt(4)
	v_mfma_f32_16x16x4_f32 v[6:9], v157, v158, v[6:9]
	s_nop 0
	s_nop 0
	s_nop 0
	s_waitcnt lgkmcnt(2)
	v_mfma_f32_16x16x4_f32 v[6:9], v159, v160, v[6:9]
	s_nop 0
	s_nop 0
	s_nop 7
	s_waitcnt lgkmcnt(1)
	v_mfma_f32_16x16x4_f32 v[20:23], v166, v6, 0
	v_mfma_f32_16x16x4_f32 v[20:23], v167, v7, v[20:23]
	s_nop 0
	s_nop 0
	s_waitcnt lgkmcnt(0)
	v_mfma_f32_16x16x4_f32 v[20:23], v168, v8, v[20:23]
	v_mfma_f32_16x16x4_f32 v[6:9], v169, v9, v[20:23]
	s_nop 9
	v_xor_b32_e32 v5, 0x80000000, v6
	ds_write_b32 v3, v5 offset:12544
	v_xor_b32_e32 v5, 0x80000000, v7
	ds_write_b32 v3, v5 offset:12804
	v_xor_b32_e32 v5, 0x80000000, v8
	ds_write_b32 v3, v5 offset:13064
	v_xor_b32_e32 v5, 0x80000000, v9
	ds_write_b32 v3, v5 offset:13324
	ds_read_b32 v233, v2 offset:8448
	ds_read_b32 v244, v4 offset:8448
	ds_read_b32 v249, v4 offset:8464
	ds_read_b32 v152, v4 offset:8480
	ds_read_b32 v153, v4 offset:8496
	ds_read_b32 v154, v2 offset:9488
	ds_read_b32 v155, v2 offset:10528
	ds_read_b32 v156, v2 offset:11568
	ds_read2_b32 v[158:159], v48 offset1:1
	ds_read2_b32 v[160:161], v11 offset1:1
	s_nop 0
	s_nop 0
	s_nop 0
	s_nop 0
	s_nop 0
	s_nop 0
	s_waitcnt lgkmcnt(8)
	v_mfma_f32_16x16x4_f32 v[4:7], v244, v233, 0
	s_nop 0
	s_nop 0
	s_waitcnt lgkmcnt(4)
	v_mfma_f32_16x16x4_f32 v[4:7], v249, v154, v[4:7]
	s_nop 0
	s_nop 0
	s_nop 0
	s_waitcnt lgkmcnt(3)
	v_mfma_f32_16x16x4_f32 v[4:7], v152, v155, v[4:7]
	s_nop 0
	s_nop 0
	s_waitcnt lgkmcnt(2)
	v_mfma_f32_16x16x4_f32 v[4:7], v153, v156, v[4:7]
	s_nop 0
	s_nop 8
	s_waitcnt lgkmcnt(1)
	v_mfma_f32_16x16x4_f32 v[20:23], v158, v4, 0
	v_mfma_f32_16x16x4_f32 v[20:23], v159, v5, v[20:23]
	s_nop 0
	s_nop 0
	s_waitcnt lgkmcnt(0)
	v_mfma_f32_16x16x4_f32 v[20:23], v160, v6, v[20:23]
	v_mfma_f32_16x16x4_f32 v[4:7], v161, v7, v[20:23]
	s_nop 9
	v_xor_b32_e32 v2, 0x80000000, v4
	ds_write_b32 v3, v2 offset:12608
	v_xor_b32_e32 v2, 0x80000000, v5
	ds_write_b32 v3, v2 offset:12868
	v_xor_b32_e32 v2, 0x80000000, v6
	ds_write_b32 v3, v2 offset:13128
	v_xor_b32_e32 v2, 0x80000000, v7
	ds_write_b32 v3, v2 offset:13388
